# v102 + XCD barrier between SwiGLU latent pass and down-projection split into arrive (after latent tiles) and wait (after the context tiles, just before the down-projection)
# speedup vs baseline: 1.0008x; 1.0008x over previous
; DI void grid_barrier(unsigned* cnt, unsigned target) {
;     asm volatile("s_waitcnt vmcnt(0) lgkmcnt(0)" ::: "memory");
;     __syncthreads();
;     if (threadIdx.x == 0) {
;         __builtin_amdgcn_fence(__ATOMIC_RELEASE, "agent");
;         asm volatile("s_waitcnt vmcnt(0)" ::: "memory");
;         __hip_atomic_fetch_add(cnt, 1u, __ATOMIC_RELAXED, __HIP_MEMORY_SCOPE_AGENT);
;         while (__hip_atomic_load(cnt, __ATOMIC_RELAXED, __HIP_MEMORY_SCOPE_AGENT) < target) __builtin_amdgcn_s_sleep(2);
;         __builtin_amdgcn_fence(__ATOMIC_ACQUIRE, "agent");
;         asm volatile("s_waitcnt vmcnt(0)" ::: "memory");
;     }
;     __syncthreads();
; }
.Lch_not2:
	s_cmp_eq_u32 s98, 3
	s_cbranch_scc0 .Lch_not3
	s_waitcnt vmcnt(0) lgkmcnt(0)
	s_barrier
	v_readlane_b32 s10, v255, 60
	s_add_u32 s10, s10, 1
	s_nop 0
	v_writelane_b32 v255, s10, 60
	s_lshl_b32 s10, s10, 5
	v_readlane_b32 s2, v255, 0
	s_mov_b64 s[4:5], exec
	v_readlane_b32 s6, v255, 3
	v_readlane_b32 s7, v255, 4
	s_and_b64 s[6:7], s[4:5], s[6:7]
	s_mov_b64 exec, s[6:7]
	s_cbranch_execz .Llb_S
	s_and_b32 s3, s2, 7
	s_lshl_b32 s3, s3, 2
	s_add_u32 s8, s14, s3
	s_addc_u32 s9, s15, 0
	v_mov_b32_e32 v0, 1
	global_atomic_add v1, v0, s[8:9] offset:128
.Llb_S:
	s_mov_b64 exec, s[4:5]
	s_barrier
	v_readlane_b32 s10, v255, 61
	s_lshl_b32 s10, s10, 6
	s_mov_b64 s[4:5], exec
	v_readlane_b32 s6, v255, 3
	v_readlane_b32 s7, v255, 4
	s_and_b64 s[6:7], s[4:5], s[6:7]
	s_mov_b64 exec, s[6:7]
	s_cbranch_execz .Lwd_C
	v_readlane_b32 s2, v255, 0
	s_bfe_u32 s2, s2, 0x20001
	s_lshl_b32 s2, s2, 2
	s_add_u32 s8, s14, s2
	s_addc_u32 s9, s15, 0

; DI void grid_barrier(unsigned* cnt, unsigned target) {
;     asm volatile("s_waitcnt vmcnt(0) lgkmcnt(0)" ::: "memory");
;     __syncthreads();
;     if (threadIdx.x == 0) {
;         __builtin_amdgcn_fence(__ATOMIC_RELEASE, "agent");
;         asm volatile("s_waitcnt vmcnt(0)" ::: "memory");
;         __hip_atomic_fetch_add(cnt, 1u, __ATOMIC_RELAXED, __HIP_MEMORY_SCOPE_AGENT);
;         while (__hip_atomic_load(cnt, __ATOMIC_RELAXED, __HIP_MEMORY_SCOPE_AGENT) < target) __builtin_amdgcn_s_sleep(2);
;         __builtin_amdgcn_fence(__ATOMIC_ACQUIRE, "agent");
;         asm volatile("s_waitcnt vmcnt(0)" ::: "memory");
;     }
;     __syncthreads();
; }
.Lar_D:
	s_mov_b64 exec, s[4:5]
	v_readlane_b32 s10, v255, 60
	s_lshl_b32 s10, s10, 5
	v_readlane_b32 s2, v255, 0
	s_mov_b64 s[4:5], exec
	v_readlane_b32 s6, v255, 3
	v_readlane_b32 s7, v255, 4
	s_and_b64 s[6:7], s[4:5], s[6:7]
	s_mov_b64 exec, s[6:7]
	s_cbranch_execz .Lwd_S
	s_and_b32 s3, s2, 7
	s_lshl_b32 s3, s3, 2
	s_add_u32 s8, s14, s3
	s_addc_u32 s9, s15, 0
